# prep_w (all remaining per-element conditional-gain loops in P0 and at the layer top): weight + gain loads batched
# speedup vs baseline: 1.0327x; 1.0117x over previous
; DI void prep_w(int vb, int nvb, const float* __restrict__ W, bf16_t* __restrict__ Wt, int K, int N, const float* __restrict__ gk, const float* __restrict__ sn, int mode, float* smf) {
;     ...
;   for (int t0 = 0; t0 < nt; t0 += nvb) {
;     const int t = t0 + vb;
;     const bool on = t < nt;
;     const int k0 = (t / ntn) * 64, n0 = (t % ntn) * 64;
;     if (on) {
; #pragma unroll
;       for (int i = 0; i < 16; ++i) {
;         const int kk = i * 4 + (tid >> 6), nn = tid & 63;
;         float v = __builtin_nontemporal_load(W + (size_t)(k0 + kk) * N + n0 + nn);
;         if (gk) v *= gk[k0 + kk];
;         if (sn) v *= sn[n0 + nn];
;         smf[kk * 65 + nn] = v;
;       }
;     }
.LBB0_105:
	s_add_i32 s4, s95, s56
	s_cmpk_lt_i32 s4, 0x120
	s_mul_hi_i32 s5, s4, 0x2aaaaaab
	s_cselect_b64 s[54:55], -1, 0
	s_lshr_b32 s38, s5, 31
	s_ashr_i32 s5, s5, 2
	s_add_i32 s5, s5, s38
	s_lshl_b32 s38, s5, 6
	s_mul_i32 s5, s5, 24
	s_sub_i32 s5, s4, s5
	s_lshl_b32 s52, s5, 6
	s_cmpk_gt_i32 s4, 0x11f
	s_cbranch_scc1 .LBB0_139
	s_ashr_i32 s53, s52, 31
	v_lshl_add_u64 v[8:9], s[52:53], 2, v[6:7]
	v_add_u32_e32 v10, s38, v14
	v_mad_i64_i32 v[12:13], s[4:5], v10, s69, v[8:9]
	global_load_dword v48, v[12:13], off nt
	v_ashrrev_i32_e32 v11, 31, v10
	v_cndmask_b32_e64 v12, 0, 1, s[20:21]
	v_cmp_ne_u32_e64 s[4:5], 1, v12
	v_lshl_add_u64 v[12:13], v[10:11], 2, s[30:31]
	v_add_u32_e32 v11, 4, v10
	v_mad_i64_i32 v[38:39], s[58:59], v11, s69, v[8:9]
	global_load_dword v49, v[38:39], off nt
	v_add_u32_e32 v36, 8, v10
	v_mad_i64_i32 v[36:37], s[58:59], v36, s69, v[8:9]
	global_load_dword v50, v[36:37], off nt
	v_add_u32_e32 v11, 12, v10
	v_mad_i64_i32 v[38:39], s[58:59], v11, s69, v[8:9]
	global_load_dword v51, v[38:39], off nt
	v_add_u32_e32 v36, 16, v10
	v_mad_i64_i32 v[36:37], s[58:59], v36, s69, v[8:9]
	global_load_dword v52, v[36:37], off nt
	v_add_u32_e32 v11, 20, v10
	v_mad_i64_i32 v[38:39], s[58:59], v11, s69, v[8:9]
	global_load_dword v53, v[38:39], off nt
	v_add_u32_e32 v36, 24, v10
	v_mad_i64_i32 v[36:37], s[58:59], v36, s69, v[8:9]
	global_load_dword v54, v[36:37], off nt
	v_add_u32_e32 v11, 28, v10
	v_mad_i64_i32 v[38:39], s[58:59], v11, s69, v[8:9]
	global_load_dword v55, v[38:39], off nt
	v_add_u32_e32 v36, 32, v10
	v_mad_i64_i32 v[36:37], s[58:59], v36, s69, v[8:9]
	global_load_dword v56, v[36:37], off nt
	v_add_u32_e32 v11, 36, v10
	v_mad_i64_i32 v[38:39], s[58:59], v11, s69, v[8:9]
	global_load_dword v57, v[38:39], off nt
	v_add_u32_e32 v36, 40, v10
	v_mad_i64_i32 v[36:37], s[58:59], v36, s69, v[8:9]
	global_load_dword v58, v[36:37], off nt
	v_add_u32_e32 v11, 44, v10
	v_mad_i64_i32 v[38:39], s[58:59], v11, s69, v[8:9]
	global_load_dword v59, v[38:39], off nt
	v_add_u32_e32 v36, 48, v10
	v_mad_i64_i32 v[36:37], s[58:59], v36, s69, v[8:9]
	global_load_dword v60, v[36:37], off nt
	v_add_u32_e32 v11, 52, v10
	v_mad_i64_i32 v[38:39], s[58:59], v11, s69, v[8:9]
	global_load_dword v61, v[38:39], off nt
	v_add_u32_e32 v36, 56, v10
	v_mad_i64_i32 v[36:37], s[58:59], v36, s69, v[8:9]
	global_load_dword v62, v[36:37], off nt
	v_add_u32_e32 v10, 60, v10
	v_mad_i64_i32 v[8:9], s[58:59], v10, s69, v[8:9]
	global_load_dword v63, v[8:9], off nt
	s_andn2_b64 vcc, exec, s[20:21]
	s_cbranch_vccnz .Lpwc105_a
	global_load_dword v64, v[12:13], off
	global_load_dword v65, v[12:13], off offset:16
	global_load_dword v83, v[12:13], off offset:32
	global_load_dword v84, v[12:13], off offset:48
	global_load_dword v85, v[12:13], off offset:64
	global_load_dword v86, v[12:13], off offset:80
	global_load_dword v87, v[12:13], off offset:96
	global_load_dword v88, v[12:13], off offset:112
	global_load_dword v89, v[12:13], off offset:128
	global_load_dword v90, v[12:13], off offset:144
	global_load_dword v91, v[12:13], off offset:160
	global_load_dword v92, v[12:13], off offset:176
	global_load_dword v93, v[12:13], off offset:192
	global_load_dword v94, v[12:13], off offset:208
	global_load_dword v95, v[12:13], off offset:224
	global_load_dword v96, v[12:13], off offset:240
	s_waitcnt vmcnt(0)
	v_mul_f32_e32 v48, v48, v64
	v_mul_f32_e32 v49, v49, v65
	v_mul_f32_e32 v50, v50, v83
	v_mul_f32_e32 v51, v51, v84
	v_mul_f32_e32 v52, v52, v85
	v_mul_f32_e32 v53, v53, v86
	v_mul_f32_e32 v54, v54, v87
	v_mul_f32_e32 v55, v55, v88
	v_mul_f32_e32 v56, v56, v89
	v_mul_f32_e32 v57, v57, v90
	v_mul_f32_e32 v58, v58, v91
	v_mul_f32_e32 v59, v59, v92
	v_mul_f32_e32 v60, v60, v93
	v_mul_f32_e32 v61, v61, v94
	v_mul_f32_e32 v62, v62, v95
	v_mul_f32_e32 v63, v63, v96
.Lpwc105_a:
	s_waitcnt vmcnt(0)
	ds_write_b32 v19, v48
	ds_write_b32 v20, v49
	ds_write_b32 v21, v50
	ds_write_b32 v22, v51
	ds_write_b32 v23, v52
	ds_write_b32 v24, v53
	ds_write_b32 v25, v54
	ds_write_b32 v26, v55
	ds_write_b32 v27, v56
	ds_write_b32 v29, v57
	ds_write_b32 v30, v58
	ds_write_b32 v31, v59
	ds_write_b32 v32, v60
	ds_write_b32 v33, v61
	ds_write_b32 v34, v62
	ds_write_b32 v35, v63

; DI void prep_w(int vb, int nvb, const float* __restrict__ W, bf16_t* __restrict__ Wt, int K, int N, const float* __restrict__ gk, const float* __restrict__ sn, int mode, float* smf) {
;     ...
;   for (int t0 = 0; t0 < nt; t0 += nvb) {
;     const int t = t0 + vb;
;     const bool on = t < nt;
;     const int k0 = (t / ntn) * 64, n0 = (t % ntn) * 64;
;     if (on) {
; #pragma unroll
;       for (int i = 0; i < 16; ++i) {
;         const int kk = i * 4 + (tid >> 6), nn = tid & 63;
;         float v = __builtin_nontemporal_load(W + (size_t)(k0 + kk) * N + n0 + nn);
;         if (gk) v *= gk[k0 + kk];
;         if (sn) v *= sn[n0 + nn];
;         smf[kk * 65 + nn] = v;
;       }
;     }
.LBB0_143:
	s_add_i32 s4, s95, s56
	s_cmpk_lt_i32 s4, 0x80
	s_cselect_b64 s[54:55], -1, 0
	s_ashr_i32 s5, s4, 31
	s_lshr_b32 s5, s5, 27
	s_add_i32 s5, s4, s5
	s_lshl_b32 s38, s5, 1
	s_and_b32 s5, s5, 0x3ffffe0
	s_sub_i32 s5, s4, s5
	s_andn2_b32 s38, s38, 63
	s_lshl_b32 s52, s5, 6
	s_cmpk_gt_i32 s4, 0x7f
	s_cbranch_scc1 .LBB0_177
	v_add_u32_e32 v12, s38, v14
	s_ashr_i32 s53, s52, 31
	v_ashrrev_i32_e32 v13, 31, v12
	v_lshl_add_u64 v[8:9], s[52:53], 2, v[6:7]
	v_lshlrev_b64 v[10:11], 13, v[12:13]
	v_lshl_add_u64 v[10:11], v[8:9], 0, v[10:11]
	global_load_dword v48, v[10:11], off nt
	v_cndmask_b32_e64 v10, 0, 1, s[22:23]
	v_cmp_ne_u32_e64 s[4:5], 1, v10
	v_lshl_add_u64 v[10:11], v[12:13], 2, s[30:31]
	v_add_u32_e32 v38, 4, v12
	v_ashrrev_i32_e32 v39, 31, v38
	v_lshlrev_b64 v[38:39], 13, v[38:39]
	v_lshl_add_u64 v[38:39], v[8:9], 0, v[38:39]
	global_load_dword v49, v[38:39], off nt
	v_add_u32_e32 v36, 8, v12
	v_ashrrev_i32_e32 v37, 31, v36
	v_lshlrev_b64 v[36:37], 13, v[36:37]
	v_lshl_add_u64 v[36:37], v[8:9], 0, v[36:37]
	global_load_dword v50, v[36:37], off nt
	v_add_u32_e32 v38, 12, v12
	v_ashrrev_i32_e32 v39, 31, v38
	v_lshlrev_b64 v[38:39], 13, v[38:39]
	v_lshl_add_u64 v[38:39], v[8:9], 0, v[38:39]
	global_load_dword v51, v[38:39], off nt
	v_add_u32_e32 v36, 16, v12
	v_ashrrev_i32_e32 v37, 31, v36
	v_lshlrev_b64 v[36:37], 13, v[36:37]
	v_lshl_add_u64 v[36:37], v[8:9], 0, v[36:37]
	global_load_dword v52, v[36:37], off nt
	v_add_u32_e32 v38, 20, v12
	v_ashrrev_i32_e32 v39, 31, v38
	v_lshlrev_b64 v[38:39], 13, v[38:39]
	v_lshl_add_u64 v[38:39], v[8:9], 0, v[38:39]
	global_load_dword v53, v[38:39], off nt
	v_add_u32_e32 v36, 24, v12
	v_ashrrev_i32_e32 v37, 31, v36
	v_lshlrev_b64 v[36:37], 13, v[36:37]
	v_lshl_add_u64 v[36:37], v[8:9], 0, v[36:37]
	global_load_dword v54, v[36:37], off nt
	v_add_u32_e32 v38, 28, v12
	v_ashrrev_i32_e32 v39, 31, v38
	v_lshlrev_b64 v[38:39], 13, v[38:39]
	v_lshl_add_u64 v[38:39], v[8:9], 0, v[38:39]
	global_load_dword v55, v[38:39], off nt
	v_add_u32_e32 v36, 32, v12
	v_ashrrev_i32_e32 v37, 31, v36
	v_lshlrev_b64 v[36:37], 13, v[36:37]
	v_lshl_add_u64 v[36:37], v[8:9], 0, v[36:37]
	global_load_dword v56, v[36:37], off nt
	v_add_u32_e32 v38, 36, v12
	v_ashrrev_i32_e32 v39, 31, v38
	v_lshlrev_b64 v[38:39], 13, v[38:39]
	v_lshl_add_u64 v[38:39], v[8:9], 0, v[38:39]
	global_load_dword v57, v[38:39], off nt
	v_add_u32_e32 v36, 40, v12
	v_ashrrev_i32_e32 v37, 31, v36
	v_lshlrev_b64 v[36:37], 13, v[36:37]
	v_lshl_add_u64 v[36:37], v[8:9], 0, v[36:37]
	global_load_dword v58, v[36:37], off nt
	v_add_u32_e32 v38, 44, v12
	v_ashrrev_i32_e32 v39, 31, v38
	v_lshlrev_b64 v[38:39], 13, v[38:39]
	v_lshl_add_u64 v[38:39], v[8:9], 0, v[38:39]
	global_load_dword v59, v[38:39], off nt
	v_add_u32_e32 v36, 48, v12
	v_ashrrev_i32_e32 v37, 31, v36
	v_lshlrev_b64 v[36:37], 13, v[36:37]
	v_lshl_add_u64 v[36:37], v[8:9], 0, v[36:37]
	global_load_dword v60, v[36:37], off nt
	v_add_u32_e32 v38, 52, v12
	v_ashrrev_i32_e32 v39, 31, v38
	v_lshlrev_b64 v[38:39], 13, v[38:39]
	v_lshl_add_u64 v[38:39], v[8:9], 0, v[38:39]
	global_load_dword v61, v[38:39], off nt
	v_add_u32_e32 v36, 56, v12
	v_ashrrev_i32_e32 v37, 31, v36
	v_lshlrev_b64 v[36:37], 13, v[36:37]
	v_lshl_add_u64 v[36:37], v[8:9], 0, v[36:37]
	global_load_dword v62, v[36:37], off nt
	v_add_u32_e32 v12, 60, v12
	v_ashrrev_i32_e32 v13, 31, v12
	v_lshlrev_b64 v[12:13], 13, v[12:13]
	v_lshl_add_u64 v[8:9], v[8:9], 0, v[12:13]
	global_load_dword v63, v[8:9], off nt
	s_andn2_b64 vcc, exec, s[22:23]
	s_cbranch_vccnz .Lpwc143_a
	global_load_dword v64, v[10:11], off
	global_load_dword v65, v[10:11], off offset:16
	global_load_dword v83, v[10:11], off offset:32
	global_load_dword v84, v[10:11], off offset:48
	global_load_dword v85, v[10:11], off offset:64
	global_load_dword v86, v[10:11], off offset:80
	global_load_dword v87, v[10:11], off offset:96
	global_load_dword v88, v[10:11], off offset:112
	global_load_dword v89, v[10:11], off offset:128
	global_load_dword v90, v[10:11], off offset:144
	global_load_dword v91, v[10:11], off offset:160
	global_load_dword v92, v[10:11], off offset:176
	global_load_dword v93, v[10:11], off offset:192
	global_load_dword v94, v[10:11], off offset:208
	global_load_dword v95, v[10:11], off offset:224
	global_load_dword v96, v[10:11], off offset:240
	s_waitcnt vmcnt(0)
	v_mul_f32_e32 v48, v48, v64
	v_mul_f32_e32 v49, v49, v65
	v_mul_f32_e32 v50, v50, v83
	v_mul_f32_e32 v51, v51, v84
	v_mul_f32_e32 v52, v52, v85
	v_mul_f32_e32 v53, v53, v86
	v_mul_f32_e32 v54, v54, v87
	v_mul_f32_e32 v55, v55, v88
	v_mul_f32_e32 v56, v56, v89
	v_mul_f32_e32 v57, v57, v90
	v_mul_f32_e32 v58, v58, v91
	v_mul_f32_e32 v59, v59, v92
	v_mul_f32_e32 v60, v60, v93
	v_mul_f32_e32 v61, v61, v94
	v_mul_f32_e32 v62, v62, v95
	v_mul_f32_e32 v63, v63, v96

; DI void prep_w(int vb, int nvb, const float* __restrict__ W, bf16_t* __restrict__ Wt, int K, int N, const float* __restrict__ gk, const float* __restrict__ sn, int mode, float* smf) {
;     ...
;   for (int t0 = 0; t0 < nt; t0 += nvb) {
;     const int t = t0 + vb;
;     const bool on = t < nt;
;     const int k0 = (t / ntn) * 64, n0 = (t % ntn) * 64;
;     if (on) {
; #pragma unroll
;       for (int i = 0; i < 16; ++i) {
;         const int kk = i * 4 + (tid >> 6), nn = tid & 63;
;         float v = __builtin_nontemporal_load(W + (size_t)(k0 + kk) * N + n0 + nn);
;         if (gk) v *= gk[k0 + kk];
;         if (sn) v *= sn[n0 + nn];
;         smf[kk * 65 + nn] = v;
;       }
;     }
.LBB0_187:
	s_add_i32 s5, s95, s14
	s_cmpk_lt_i32 s5, 0x2c0
	s_mul_hi_i32 s4, s5, 0x2e8ba2e9
	s_cselect_b64 s[12:13], -1, 0
	s_lshr_b32 s6, s4, 31
	s_ashr_i32 s4, s4, 3
	s_add_i32 s6, s4, s6
	s_lshl_b32 s4, s6, 6
	s_mul_i32 s6, s6, 44
	s_sub_i32 s6, s5, s6
	s_lshl_b32 s6, s6, 6
	s_cmpk_gt_i32 s5, 0x2bf
	s_cbranch_scc1 .LBB0_221
	s_ashr_i32 s7, s6, 31
	v_lshl_add_u64 v[6:7], s[6:7], 2, v[4:5]
	v_add_u32_e32 v8, s4, v1
	v_mad_i64_i32 v[10:11], s[18:19], v8, s15, v[6:7]
	global_load_dword v44, v[10:11], off nt
	v_ashrrev_i32_e32 v9, 31, v8
	v_lshl_add_u64 v[10:11], v[8:9], 2, s[40:41]
	v_add_u32_e32 v9, 4, v8
	v_mad_i64_i32 v[36:37], s[18:19], v9, s15, v[6:7]
	global_load_dword v45, v[36:37], off nt
	v_add_u32_e32 v35, 8, v8
	v_mad_i64_i32 v[36:37], s[18:19], v35, s15, v[6:7]
	global_load_dword v46, v[36:37], off nt
	v_add_u32_e32 v9, 12, v8
	v_mad_i64_i32 v[36:37], s[18:19], v9, s15, v[6:7]
	global_load_dword v47, v[36:37], off nt
	v_add_u32_e32 v35, 16, v8
	v_mad_i64_i32 v[36:37], s[18:19], v35, s15, v[6:7]
	global_load_dword v48, v[36:37], off nt
	v_add_u32_e32 v9, 20, v8
	v_mad_i64_i32 v[36:37], s[18:19], v9, s15, v[6:7]
	global_load_dword v49, v[36:37], off nt
	v_add_u32_e32 v35, 24, v8
	v_mad_i64_i32 v[36:37], s[18:19], v35, s15, v[6:7]
	global_load_dword v50, v[36:37], off nt
	v_add_u32_e32 v9, 28, v8
	v_mad_i64_i32 v[36:37], s[18:19], v9, s15, v[6:7]
	global_load_dword v51, v[36:37], off nt
	v_add_u32_e32 v35, 32, v8
	v_mad_i64_i32 v[36:37], s[18:19], v35, s15, v[6:7]
	global_load_dword v52, v[36:37], off nt
	v_add_u32_e32 v9, 36, v8
	v_mad_i64_i32 v[36:37], s[18:19], v9, s15, v[6:7]
	global_load_dword v53, v[36:37], off nt
	v_add_u32_e32 v35, 40, v8
	v_mad_i64_i32 v[36:37], s[18:19], v35, s15, v[6:7]
	global_load_dword v54, v[36:37], off nt
	v_add_u32_e32 v9, 44, v8
	v_mad_i64_i32 v[36:37], s[18:19], v9, s15, v[6:7]
	global_load_dword v55, v[36:37], off nt
	v_add_u32_e32 v35, 48, v8
	v_mad_i64_i32 v[36:37], s[18:19], v35, s15, v[6:7]
	global_load_dword v56, v[36:37], off nt
	v_add_u32_e32 v9, 52, v8
	v_mad_i64_i32 v[36:37], s[18:19], v9, s15, v[6:7]
	global_load_dword v57, v[36:37], off nt
	v_add_u32_e32 v35, 56, v8
	v_mad_i64_i32 v[36:37], s[18:19], v35, s15, v[6:7]
	global_load_dword v58, v[36:37], off nt
	v_add_u32_e32 v8, 60, v8
	v_mad_i64_i32 v[6:7], s[18:19], v8, s15, v[6:7]
	global_load_dword v59, v[6:7], off nt
	s_and_b64 vcc, exec, s[0:1]
	s_cbranch_vccnz .Lpwc187_a
	global_load_dword v60, v[10:11], off
	global_load_dword v61, v[10:11], off offset:16
	global_load_dword v62, v[10:11], off offset:32
	global_load_dword v63, v[10:11], off offset:48
	global_load_dword v64, v[10:11], off offset:64
	global_load_dword v65, v[10:11], off offset:80
	global_load_dword v66, v[10:11], off offset:96
	global_load_dword v67, v[10:11], off offset:112
	global_load_dword v68, v[10:11], off offset:128
	global_load_dword v69, v[10:11], off offset:144
	global_load_dword v70, v[10:11], off offset:160
	global_load_dword v71, v[10:11], off offset:176
	global_load_dword v72, v[10:11], off offset:192
	global_load_dword v73, v[10:11], off offset:208
	global_load_dword v74, v[10:11], off offset:224
	global_load_dword v75, v[10:11], off offset:240
	s_waitcnt vmcnt(0)
	v_mul_f32_e32 v44, v44, v60
	v_mul_f32_e32 v45, v45, v61
	v_mul_f32_e32 v46, v46, v62
	v_mul_f32_e32 v47, v47, v63
	v_mul_f32_e32 v48, v48, v64
	v_mul_f32_e32 v49, v49, v65
	v_mul_f32_e32 v50, v50, v66
	v_mul_f32_e32 v51, v51, v67
	v_mul_f32_e32 v52, v52, v68
	v_mul_f32_e32 v53, v53, v69
	v_mul_f32_e32 v54, v54, v70
	v_mul_f32_e32 v55, v55, v71
	v_mul_f32_e32 v56, v56, v72
	v_mul_f32_e32 v57, v57, v73
	v_mul_f32_e32 v58, v58, v74
	v_mul_f32_e32 v59, v59, v75
.Lpwc187_a:
	s_waitcnt vmcnt(0)
	ds_write_b32 v15, v44
	ds_write_b32 v16, v45
	ds_write_b32 v17, v46
	ds_write_b32 v18, v47
	ds_write_b32 v19, v48
	ds_write_b32 v20, v49
	ds_write_b32 v21, v50
	ds_write_b32 v22, v51
	ds_write_b32 v23, v52
	ds_write_b32 v24, v53
	ds_write_b32 v25, v54
	ds_write_b32 v26, v55
	ds_write_b32 v27, v56
	ds_write_b32 v29, v57
	ds_write_b32 v30, v58
	ds_write_b32 v31, v59

; DI void prep_w(int vb, int nvb, const float* __restrict__ W, bf16_t* __restrict__ Wt, int K, int N, const float* __restrict__ gk, const float* __restrict__ sn, int mode, float* smf) {
;     ...
;       for (int i = 0; i < 16; ++i) {
;         const int kk = i * 4 + (tid >> 6), nn = tid & 63;
;         float v = __builtin_nontemporal_load(W + (size_t)(k0 + kk) * N + n0 + nn);
;         if (gk) v *= gk[k0 + kk];
;         if (sn) v *= sn[n0 + nn];
;         smf[kk * 65 + nn] = v;
.Lpwc225_a:
	s_waitcnt vmcnt(0)
	ds_write_b32 v14, v44
	ds_write_b32 v15, v45
	ds_write_b32 v16, v46
	ds_write_b32 v17, v47
	ds_write_b32 v18, v48
	ds_write_b32 v19, v49
	ds_write_b32 v20, v50
	ds_write_b32 v21, v51
	ds_write_b32 v22, v52
	ds_write_b32 v23, v53
	ds_write_b32 v24, v54
	ds_write_b32 v25, v55
	ds_write_b32 v26, v56
	ds_write_b32 v27, v57
	ds_write_b32 v29, v58
	ds_write_b32 v30, v59

; DI void prep_w(int vb, int nvb, const float* __restrict__ W, bf16_t* __restrict__ Wt, int K, int N, const float* __restrict__ gk, const float* __restrict__ sn, int mode, float* smf) {
;     ...
;   for (int t0 = 0; t0 < nt; t0 += nvb) {
;     const int t = t0 + vb;
;     const bool on = t < nt;
;     const int k0 = (t / ntn) * 64, n0 = (t % ntn) * 64;
;     if (on) {
; #pragma unroll
;       for (int i = 0; i < 16; ++i) {
;         const int kk = i * 4 + (tid >> 6), nn = tid & 63;
;         float v = __builtin_nontemporal_load(W + (size_t)(k0 + kk) * N + n0 + nn);
;         if (gk) v *= gk[k0 + kk];
;         if (sn) v *= sn[n0 + nn];
;         smf[kk * 65 + nn] = v;
;       }
;     }
.LBB0_269:
	s_add_i32 s1, s95, s12
	s_cmpk_lt_i32 s1, 0x2c0
	s_mul_hi_i32 s0, s1, 0x2e8ba2e9
	s_cselect_b64 s[6:7], -1, 0
	s_lshr_b32 s4, s0, 31
	s_ashr_i32 s0, s0, 3
	s_add_i32 s4, s0, s4
	s_lshl_b32 s0, s4, 6
	s_mul_i32 s4, s4, 44
	s_sub_i32 s4, s1, s4
	s_lshl_b32 s4, s4, 6
	s_cmpk_gt_i32 s1, 0x2bf
	s_cbranch_scc1 .LBB0_303
	s_ashr_i32 s5, s4, 31
	v_lshl_add_u64 v[6:7], s[4:5], 2, v[4:5]
	v_add_u32_e32 v8, s0, v1
	v_mad_i64_i32 v[10:11], s[22:23], v8, s13, v[6:7]
	global_load_dword v44, v[10:11], off nt
	v_ashrrev_i32_e32 v9, 31, v8
	v_lshl_add_u64 v[10:11], v[8:9], 2, s[78:79]
	v_add_u32_e32 v9, 4, v8
	v_mad_i64_i32 v[36:37], s[22:23], v9, s13, v[6:7]
	global_load_dword v45, v[36:37], off nt
	v_add_u32_e32 v35, 8, v8
	v_mad_i64_i32 v[36:37], s[22:23], v35, s13, v[6:7]
	global_load_dword v46, v[36:37], off nt
	v_add_u32_e32 v9, 12, v8
	v_mad_i64_i32 v[36:37], s[22:23], v9, s13, v[6:7]
	global_load_dword v47, v[36:37], off nt
	v_add_u32_e32 v35, 16, v8
	v_mad_i64_i32 v[36:37], s[22:23], v35, s13, v[6:7]
	global_load_dword v48, v[36:37], off nt
	v_add_u32_e32 v9, 20, v8
	v_mad_i64_i32 v[36:37], s[22:23], v9, s13, v[6:7]
	global_load_dword v49, v[36:37], off nt
	v_add_u32_e32 v35, 24, v8
	v_mad_i64_i32 v[36:37], s[22:23], v35, s13, v[6:7]
	global_load_dword v50, v[36:37], off nt
	v_add_u32_e32 v9, 28, v8
	v_mad_i64_i32 v[36:37], s[22:23], v9, s13, v[6:7]
	global_load_dword v51, v[36:37], off nt
	v_add_u32_e32 v35, 32, v8
	v_mad_i64_i32 v[36:37], s[22:23], v35, s13, v[6:7]
	global_load_dword v52, v[36:37], off nt
	v_add_u32_e32 v9, 36, v8
	v_mad_i64_i32 v[36:37], s[22:23], v9, s13, v[6:7]
	global_load_dword v53, v[36:37], off nt
	v_add_u32_e32 v35, 40, v8
	v_mad_i64_i32 v[36:37], s[22:23], v35, s13, v[6:7]
	global_load_dword v54, v[36:37], off nt
	v_add_u32_e32 v9, 44, v8
	v_mad_i64_i32 v[36:37], s[22:23], v9, s13, v[6:7]
	global_load_dword v55, v[36:37], off nt
	v_add_u32_e32 v35, 48, v8
	v_mad_i64_i32 v[36:37], s[22:23], v35, s13, v[6:7]
	global_load_dword v56, v[36:37], off nt
	v_add_u32_e32 v9, 52, v8
	v_mad_i64_i32 v[36:37], s[22:23], v9, s13, v[6:7]
	global_load_dword v57, v[36:37], off nt
	v_add_u32_e32 v35, 56, v8
	v_mad_i64_i32 v[36:37], s[22:23], v35, s13, v[6:7]
	global_load_dword v58, v[36:37], off nt
	v_add_u32_e32 v8, 60, v8
	v_mad_i64_i32 v[6:7], s[22:23], v8, s13, v[6:7]
	global_load_dword v59, v[6:7], off nt
	s_and_b64 vcc, exec, s[16:17]
	s_cbranch_vccnz .Lpwc269_a
	global_load_dword v60, v[10:11], off
	global_load_dword v61, v[10:11], off offset:16
	global_load_dword v62, v[10:11], off offset:32
	global_load_dword v63, v[10:11], off offset:48
	global_load_dword v64, v[10:11], off offset:64
	global_load_dword v65, v[10:11], off offset:80
	global_load_dword v66, v[10:11], off offset:96
	global_load_dword v67, v[10:11], off offset:112
	global_load_dword v68, v[10:11], off offset:128
	global_load_dword v69, v[10:11], off offset:144
	global_load_dword v70, v[10:11], off offset:160
	global_load_dword v71, v[10:11], off offset:176
	global_load_dword v72, v[10:11], off offset:192
	global_load_dword v73, v[10:11], off offset:208
	global_load_dword v74, v[10:11], off offset:224
	global_load_dword v75, v[10:11], off offset:240
	s_waitcnt vmcnt(0)
	v_mul_f32_e32 v44, v44, v60
	v_mul_f32_e32 v45, v45, v61
	v_mul_f32_e32 v46, v46, v62
	v_mul_f32_e32 v47, v47, v63
	v_mul_f32_e32 v48, v48, v64
	v_mul_f32_e32 v49, v49, v65
	v_mul_f32_e32 v50, v50, v66
	v_mul_f32_e32 v51, v51, v67
	v_mul_f32_e32 v52, v52, v68
	v_mul_f32_e32 v53, v53, v69
	v_mul_f32_e32 v54, v54, v70
	v_mul_f32_e32 v55, v55, v71
	v_mul_f32_e32 v56, v56, v72
	v_mul_f32_e32 v57, v57, v73
	v_mul_f32_e32 v58, v58, v74
	v_mul_f32_e32 v59, v59, v75

; DI void prep_w(int vb, int nvb, const float* __restrict__ W, bf16_t* __restrict__ Wt, int K, int N, const float* __restrict__ gk, const float* __restrict__ sn, int mode, float* smf) {
;     ...
;   for (int t0 = 0; t0 < nt; t0 += nvb) {
;     const int t = t0 + vb;
;     const bool on = t < nt;
;     const int k0 = (t / ntn) * 64, n0 = (t % ntn) * 64;
;     if (on) {
; #pragma unroll
;       for (int i = 0; i < 16; ++i) {
;         const int kk = i * 4 + (tid >> 6), nn = tid & 63;
;         float v = __builtin_nontemporal_load(W + (size_t)(k0 + kk) * N + n0 + nn);
;         if (gk) v *= gk[k0 + kk];
;         if (sn) v *= sn[n0 + nn];
;         smf[kk * 65 + nn] = v;
;       }
;     }
.LBB0_374:
	s_add_i32 s3, s95, s2
	s_cmpk_lt_i32 s3, 0x2c0
	s_mul_hi_i32 s6, s3, 0x2e8ba2e9
	s_cselect_b64 s[14:15], -1, 0
	s_lshr_b32 s7, s6, 31
	s_ashr_i32 s6, s6, 3
	s_add_i32 s7, s6, s7
	s_lshl_b32 s6, s7, 6
	s_mul_i32 s7, s7, 44
	s_sub_i32 s7, s3, s7
	s_lshl_b32 s10, s7, 6
	s_cmpk_gt_i32 s3, 0x2bf
	s_cbranch_scc1 .LBB0_408
	s_ashr_i32 s11, s10, 31
	v_lshl_add_u64 v[4:5], s[10:11], 2, v[2:3]
	v_add_u32_e32 v6, s6, v10
	v_mad_i64_i32 v[8:9], s[38:39], v6, s73, v[4:5]
	global_load_dword v42, v[8:9], off nt
	v_ashrrev_i32_e32 v7, 31, v6
	v_lshl_add_u64 v[8:9], v[6:7], 2, s[4:5]
	v_add_u32_e32 v7, 4, v6
	v_mad_i64_i32 v[34:35], s[38:39], v7, s73, v[4:5]
	global_load_dword v43, v[34:35], off nt
	v_add_u32_e32 v33, 8, v6
	v_mad_i64_i32 v[34:35], s[38:39], v33, s73, v[4:5]
	global_load_dword v44, v[34:35], off nt
	v_add_u32_e32 v7, 12, v6
	v_mad_i64_i32 v[34:35], s[38:39], v7, s73, v[4:5]
	global_load_dword v45, v[34:35], off nt
	v_add_u32_e32 v33, 16, v6
	v_mad_i64_i32 v[34:35], s[38:39], v33, s73, v[4:5]
	global_load_dword v46, v[34:35], off nt
	v_add_u32_e32 v7, 20, v6
	v_mad_i64_i32 v[34:35], s[38:39], v7, s73, v[4:5]
	global_load_dword v47, v[34:35], off nt
	v_add_u32_e32 v33, 24, v6
	v_mad_i64_i32 v[34:35], s[38:39], v33, s73, v[4:5]
	global_load_dword v48, v[34:35], off nt
	v_add_u32_e32 v7, 28, v6
	v_mad_i64_i32 v[34:35], s[38:39], v7, s73, v[4:5]
	global_load_dword v49, v[34:35], off nt
	v_add_u32_e32 v33, 32, v6
	v_mad_i64_i32 v[34:35], s[38:39], v33, s73, v[4:5]
	global_load_dword v50, v[34:35], off nt
	v_add_u32_e32 v7, 36, v6
	v_mad_i64_i32 v[34:35], s[38:39], v7, s73, v[4:5]
	global_load_dword v51, v[34:35], off nt
	v_add_u32_e32 v33, 40, v6
	v_mad_i64_i32 v[34:35], s[38:39], v33, s73, v[4:5]
	global_load_dword v52, v[34:35], off nt
	v_add_u32_e32 v7, 44, v6
	v_mad_i64_i32 v[34:35], s[38:39], v7, s73, v[4:5]
	global_load_dword v53, v[34:35], off nt
	v_add_u32_e32 v33, 48, v6
	v_mad_i64_i32 v[34:35], s[38:39], v33, s73, v[4:5]
	global_load_dword v54, v[34:35], off nt
	v_add_u32_e32 v7, 52, v6
	v_mad_i64_i32 v[34:35], s[38:39], v7, s73, v[4:5]
	global_load_dword v55, v[34:35], off nt
	v_add_u32_e32 v33, 56, v6
	v_mad_i64_i32 v[34:35], s[38:39], v33, s73, v[4:5]
	global_load_dword v56, v[34:35], off nt
	v_add_u32_e32 v6, 60, v6
	v_mad_i64_i32 v[4:5], s[38:39], v6, s73, v[4:5]
	global_load_dword v57, v[4:5], off nt
	s_and_b64 vcc, exec, s[16:17]
	s_cbranch_vccnz .Lpwc374_a
	global_load_dword v58, v[8:9], off
	global_load_dword v59, v[8:9], off offset:16
	global_load_dword v60, v[8:9], off offset:32
	global_load_dword v61, v[8:9], off offset:48
	global_load_dword v62, v[8:9], off offset:64
	global_load_dword v63, v[8:9], off offset:80
	global_load_dword v64, v[8:9], off offset:96
	global_load_dword v65, v[8:9], off offset:112
	global_load_dword v66, v[8:9], off offset:128
	global_load_dword v67, v[8:9], off offset:144
	global_load_dword v68, v[8:9], off offset:160
	global_load_dword v69, v[8:9], off offset:176
	global_load_dword v70, v[8:9], off offset:192
	global_load_dword v71, v[8:9], off offset:208
	global_load_dword v72, v[8:9], off offset:224
	global_load_dword v73, v[8:9], off offset:240
	s_waitcnt vmcnt(0)
	v_mul_f32_e32 v42, v42, v58
	v_mul_f32_e32 v43, v43, v59
	v_mul_f32_e32 v44, v44, v60
	v_mul_f32_e32 v45, v45, v61
	v_mul_f32_e32 v46, v46, v62
	v_mul_f32_e32 v47, v47, v63
	v_mul_f32_e32 v48, v48, v64
	v_mul_f32_e32 v49, v49, v65
	v_mul_f32_e32 v50, v50, v66
	v_mul_f32_e32 v51, v51, v67
	v_mul_f32_e32 v52, v52, v68
	v_mul_f32_e32 v53, v53, v69
	v_mul_f32_e32 v54, v54, v70
	v_mul_f32_e32 v55, v55, v71
	v_mul_f32_e32 v56, v56, v72
	v_mul_f32_e32 v57, v57, v73
.Lpwc374_a:
	s_waitcnt vmcnt(0)
	ds_write_b32 v14, v42
	ds_write_b32 v15, v43
	ds_write_b32 v16, v44
	ds_write_b32 v17, v45
	ds_write_b32 v18, v46
	ds_write_b32 v19, v47
	ds_write_b32 v20, v48
	ds_write_b32 v21, v49
	ds_write_b32 v22, v50
	ds_write_b32 v23, v51
	ds_write_b32 v24, v52
	ds_write_b32 v25, v53
	ds_write_b32 v26, v54
	ds_write_b32 v27, v55
	ds_write_b32 v28, v56
	ds_write_b32 v29, v57

; DI void prep_w(int vb, int nvb, const float* __restrict__ W, bf16_t* __restrict__ Wt, int K, int N, const float* __restrict__ gk, const float* __restrict__ sn, int mode, float* smf) {
;     ...
;   for (int t0 = 0; t0 < nt; t0 += nvb) {
;     const int t = t0 + vb;
;     const bool on = t < nt;
;     const int k0 = (t / ntn) * 64, n0 = (t % ntn) * 64;
;     if (on) {
; #pragma unroll
;       for (int i = 0; i < 16; ++i) {
;         const int kk = i * 4 + (tid >> 6), nn = tid & 63;
;         float v = __builtin_nontemporal_load(W + (size_t)(k0 + kk) * N + n0 + nn);
;         if (gk) v *= gk[k0 + kk];
;         if (sn) v *= sn[n0 + nn];
;         smf[kk * 65 + nn] = v;
;       }
;     }
.LBB0_412:
	s_add_i32 s3, s95, s2
	s_cmpk_lt_i32 s3, 0x2c0
	s_mul_hi_i32 s6, s3, 0x2e8ba2e9
	s_cselect_b64 s[14:15], -1, 0
	s_lshr_b32 s7, s6, 31
	s_ashr_i32 s6, s6, 3
	s_add_i32 s7, s6, s7
	s_lshl_b32 s6, s7, 6
	s_mul_i32 s7, s7, 44
	s_sub_i32 s7, s3, s7
	s_lshl_b32 s10, s7, 6
	s_cmpk_gt_i32 s3, 0x2bf
	s_cbranch_scc1 .LBB0_446
	s_ashr_i32 s11, s10, 31
	v_lshl_add_u64 v[4:5], s[10:11], 2, v[2:3]
	v_add_u32_e32 v6, s6, v10
	v_mad_i64_i32 v[8:9], s[38:39], v6, s73, v[4:5]
	global_load_dword v40, v[8:9], off nt
	v_ashrrev_i32_e32 v7, 31, v6
	v_lshl_add_u64 v[8:9], v[6:7], 2, s[4:5]
	v_add_u32_e32 v7, 4, v6
	v_mad_i64_i32 v[32:33], s[38:39], v7, s73, v[4:5]
	global_load_dword v41, v[32:33], off nt
	v_add_u32_e32 v30, 8, v6
	v_mad_i64_i32 v[30:31], s[38:39], v30, s73, v[4:5]
	global_load_dword v42, v[30:31], off nt
	v_add_u32_e32 v7, 12, v6
	v_mad_i64_i32 v[32:33], s[38:39], v7, s73, v[4:5]
	global_load_dword v43, v[32:33], off nt
	v_add_u32_e32 v30, 16, v6
	v_mad_i64_i32 v[30:31], s[38:39], v30, s73, v[4:5]
	global_load_dword v44, v[30:31], off nt
	v_add_u32_e32 v7, 20, v6
	v_mad_i64_i32 v[32:33], s[38:39], v7, s73, v[4:5]
	global_load_dword v45, v[32:33], off nt
	v_add_u32_e32 v30, 24, v6
	v_mad_i64_i32 v[30:31], s[38:39], v30, s73, v[4:5]
	global_load_dword v46, v[30:31], off nt
	v_add_u32_e32 v7, 28, v6
	v_mad_i64_i32 v[32:33], s[38:39], v7, s73, v[4:5]
	global_load_dword v47, v[32:33], off nt
	v_add_u32_e32 v30, 32, v6
	v_mad_i64_i32 v[30:31], s[38:39], v30, s73, v[4:5]
	global_load_dword v48, v[30:31], off nt
	v_add_u32_e32 v7, 36, v6
	v_mad_i64_i32 v[32:33], s[38:39], v7, s73, v[4:5]
	global_load_dword v49, v[32:33], off nt
	v_add_u32_e32 v30, 40, v6
	v_mad_i64_i32 v[30:31], s[38:39], v30, s73, v[4:5]
	global_load_dword v50, v[30:31], off nt
	v_add_u32_e32 v7, 44, v6
	v_mad_i64_i32 v[32:33], s[38:39], v7, s73, v[4:5]
	global_load_dword v51, v[32:33], off nt
	v_add_u32_e32 v30, 48, v6
	v_mad_i64_i32 v[30:31], s[38:39], v30, s73, v[4:5]
	global_load_dword v52, v[30:31], off nt
	v_add_u32_e32 v7, 52, v6
	v_mad_i64_i32 v[32:33], s[38:39], v7, s73, v[4:5]
	global_load_dword v53, v[32:33], off nt
	v_add_u32_e32 v30, 56, v6
	v_mad_i64_i32 v[30:31], s[38:39], v30, s73, v[4:5]
	global_load_dword v54, v[30:31], off nt
	v_add_u32_e32 v6, 60, v6
	v_mad_i64_i32 v[4:5], s[38:39], v6, s73, v[4:5]
	global_load_dword v55, v[4:5], off nt
	s_and_b64 vcc, exec, s[16:17]
	s_cbranch_vccnz .Lpwc412_a
	global_load_dword v56, v[8:9], off
	global_load_dword v57, v[8:9], off offset:16
	global_load_dword v58, v[8:9], off offset:32
	global_load_dword v59, v[8:9], off offset:48
	global_load_dword v60, v[8:9], off offset:64
	global_load_dword v61, v[8:9], off offset:80
	global_load_dword v62, v[8:9], off offset:96
	global_load_dword v63, v[8:9], off offset:112
	global_load_dword v64, v[8:9], off offset:128
	global_load_dword v65, v[8:9], off offset:144
	global_load_dword v66, v[8:9], off offset:160
	global_load_dword v67, v[8:9], off offset:176
	global_load_dword v68, v[8:9], off offset:192
	global_load_dword v69, v[8:9], off offset:208
	global_load_dword v70, v[8:9], off offset:224
	global_load_dword v71, v[8:9], off offset:240
	s_waitcnt vmcnt(0)
	v_mul_f32_e32 v40, v40, v56
	v_mul_f32_e32 v41, v41, v57
	v_mul_f32_e32 v42, v42, v58
	v_mul_f32_e32 v43, v43, v59
	v_mul_f32_e32 v44, v44, v60
	v_mul_f32_e32 v45, v45, v61
	v_mul_f32_e32 v46, v46, v62
	v_mul_f32_e32 v47, v47, v63
	v_mul_f32_e32 v48, v48, v64
	v_mul_f32_e32 v49, v49, v65
	v_mul_f32_e32 v50, v50, v66
	v_mul_f32_e32 v51, v51, v67
	v_mul_f32_e32 v52, v52, v68
	v_mul_f32_e32 v53, v53, v69
	v_mul_f32_e32 v54, v54, v70
	v_mul_f32_e32 v55, v55, v71
.Lpwc412_a:
	s_waitcnt vmcnt(0)
	ds_write_b32 v13, v40
	ds_write_b32 v14, v41
	ds_write_b32 v15, v42
	ds_write_b32 v16, v43
	ds_write_b32 v17, v44
	ds_write_b32 v18, v45
	ds_write_b32 v19, v46
	ds_write_b32 v20, v47
	ds_write_b32 v21, v48
	ds_write_b32 v22, v49
	ds_write_b32 v23, v50
	ds_write_b32 v24, v51
	ds_write_b32 v25, v52
	ds_write_b32 v26, v53
	ds_write_b32 v27, v54
	ds_write_b32 v28, v55
